# w_in weight-prep loop: 8 serialized load+wait pairs batched into one wait; MLA trailing half stages tile n+1 to LDS after QK step 8 so its ds_write latency hides under the last six QK MFMAs before its
# speedup vs baseline: 1.0540x; 1.0100x over previous
; DEV unsigned cvtpk(float lo, float hi) { f32x2 v = {lo, hi}; bf16x2_t b = __builtin_convertvector(v, bf16x2_t); return __builtin_bit_cast(unsigned, b); }
; template <int MAP>
; DEV void prep_w(bf16_t* __restrict__ dst, int Nd, int K, const float* __restrict__ src, const float* __restrict__ src2, int Ns, const float* __restrict__ gain, int gtid, int gsz) {
;     ...
;     float v[8];
; #pragma unroll
;     for (int i = 0; i < 8; ++i) { const int k = kb * 8 + i; v[i] = zero ? 0.f : s[(size_t)k * Ns + sc] * (gain ? gain[k] : 1.f); }
;     u32x4 w = {cvtpk(v[0], v[1]), cvtpk(v[2], v[3]), cvtpk(v[4], v[5]), cvtpk(v[6], v[7])};
;     *(u32x4*)(dst + (size_t)n * K + kb * 8) = w;
.LBB0_17:
	s_mov_b64 s[2:3], s[68:69]
	s_mul_i32 s42, s48, 0x2960000
	s_lshl_b32 s50, s48, 10
	s_mov_b32 s51, s43
	s_and_saveexec_b64 s[52:53], s[20:21]
	s_cbranch_execz .LBB0_66
	v_readlane_b32 s4, v249, 10
	s_mul_i32 s24, s48, 0x1cc0000
	v_readlane_b32 s10, v249, 16
	v_readlane_b32 s11, v249, 17
	s_add_u32 s54, s10, s24
	v_readlane_b32 s8, v249, 14
	s_addc_u32 s55, s11, 0
	s_lshl_b64 s[24:25], s[50:51], 2
	v_readlane_b32 s9, v249, 15
	s_add_u32 s56, s8, s24
	s_addc_u32 s57, s9, s25
	s_lshl_b32 s49, s28, 6
	s_lshl_b32 s97, s28, 5
	v_lshl_add_u64 v[42:43], v[4:5], 0, s[42:43]
	s_lshl_b64 s[60:61], s[28:29], 11
	s_mov_b64 s[62:63], 0
	v_mov_b32_e32 v23, v59
	v_mov_b32_e32 v61, v58
	s_mov_b64 s[68:69], 0
	v_mov_b64_e32 v[44:45], v[0:1]
	v_readlane_b32 s5, v249, 11
	v_readlane_b32 s6, v249, 12
	v_readlane_b32 s7, v249, 13
	v_readlane_b32 s12, v249, 18
	v_readlane_b32 s13, v249, 19
	v_readlane_b32 s14, v249, 20
	v_readlane_b32 s15, v249, 21
	v_readlane_b32 s16, v249, 22
	v_readlane_b32 s17, v249, 23
	v_readlane_b32 s18, v249, 24
	v_readlane_b32 s19, v249, 25
	s_branch .LBB0_22
.LBB0_21:
	s_or_b64 exec, exec, s[70:71]
	v_cvt_pk_bf16_f32 v50, v24, v52
	v_cvt_pk_bf16_f32 v51, v53, v54
	v_cvt_pk_bf16_f32 v52, v55, v62
	v_mad_u64_u32 v[54:55], s[24:25], v46, s81, 0
	v_lshlrev_b64 v[48:49], 1, v[48:49]
	v_mov_b32_e32 v24, v55
	v_mad_u64_u32 v[46:47], s[24:25], v47, s81, v[24:25]
	v_sub_co_u32_e32 v48, vcc, v48, v54
	s_add_u32 s68, s68, s28
	s_nop 0
	v_subb_co_u32_e32 v49, vcc, v49, v46, vcc
	v_cvt_pk_bf16_f32 v53, v63, v64
	v_lshl_add_u64 v[46:47], v[42:43], 0, v[48:49]
	s_addc_u32 s69, s69, s29
	global_store_dwordx4 v[46:47], v[50:53], off
	v_lshl_add_u64 v[46:47], v[0:1], 0, s[68:69]
	s_mov_b64 s[24:25], 0xe7fff
	v_cmp_lt_i64_e32 vcc, s[24:25], v[46:47]
	v_lshl_add_u64 v[44:45], v[44:45], 0, s[28:29]
	v_add_u32_e32 v61, s49, v61
	v_add_u32_e32 v23, s97, v23
	s_or_b64 s[62:63], vcc, s[62:63]
	v_lshl_add_u64 v[42:43], v[42:43], 0, s[60:61]
	s_andn2_b64 exec, exec, s[62:63]
	s_cbranch_execz .LBB0_66

; DEV unsigned cvtpk(float lo, float hi) { f32x2 v = {lo, hi}; bf16x2_t b = __builtin_convertvector(v, bf16x2_t); return __builtin_bit_cast(unsigned, b); }
; template <int MAP>
; DEV void prep_w(bf16_t* __restrict__ dst, int Nd, int K, const float* __restrict__ src, const float* __restrict__ src2, int Ns, const float* __restrict__ gain, int gtid, int gsz) {
;     ...
;     float v[8];
; #pragma unroll
;     for (int i = 0; i < 8; ++i) { const int k = kb * 8 + i; v[i] = zero ? 0.f : s[(size_t)k * Ns + sc] * (gain ? gain[k] : 1.f); }
;     u32x4 w = {cvtpk(v[0], v[1]), cvtpk(v[2], v[3]), cvtpk(v[4], v[5]), cvtpk(v[6], v[7])};
.LBB0_28:
	s_or_b64 exec, exec, s[26:27]
	v_lshlrev_b32_e32 v48, 3, v46
	v_ashrrev_i32_e32 v51, 31, v50
	v_cndmask_b32_e64 v52, 0, 1, s[30:31]
	v_lshl_add_u64 v[50:51], v[50:51], 2, s[54:55]
	v_mov_b32_e32 v24, 0
	v_ashrrev_i32_e32 v49, 31, v48
	v_cmp_ne_u32_e64 s[26:27], 1, v52
	v_mov_b32_e32 v52, 0
	v_mov_b32_e32 v53, 0
	v_mov_b32_e32 v54, 0
	v_mov_b32_e32 v55, 0
	v_mov_b32_e32 v62, 0
	v_mov_b32_e32 v63, 0
	v_mov_b32_e32 v64, 0
	s_and_saveexec_b64 s[70:71], s[24:25]
	s_cbranch_execz .LBB0_21
	v_mad_i64_i32 v[80:81], vcc, v48, s80, v[50:51]
	global_load_dword v24, v[80:81], off
	v_or_b32_e32 v82, 1, v48
	v_mad_i64_i32 v[80:81], vcc, v82, s80, v[50:51]
	global_load_dword v52, v[80:81], off
	v_or_b32_e32 v82, 2, v48
	v_mad_i64_i32 v[80:81], vcc, v82, s80, v[50:51]
	global_load_dword v53, v[80:81], off
	v_or_b32_e32 v82, 3, v48
	v_mad_i64_i32 v[80:81], vcc, v82, s80, v[50:51]
	global_load_dword v54, v[80:81], off
	v_or_b32_e32 v82, 4, v48
	v_mad_i64_i32 v[80:81], vcc, v82, s80, v[50:51]
	global_load_dword v55, v[80:81], off
	v_or_b32_e32 v82, 5, v48
	v_mad_i64_i32 v[80:81], vcc, v82, s80, v[50:51]
	global_load_dword v62, v[80:81], off
	v_or_b32_e32 v82, 6, v48
	v_mad_i64_i32 v[80:81], vcc, v82, s80, v[50:51]
	global_load_dword v63, v[80:81], off
	v_or_b32_e32 v82, 7, v48
	v_mad_i64_i32 v[80:81], vcc, v82, s80, v[50:51]
	global_load_dword v64, v[80:81], off
	v_mov_b32_e32 v84, 1.0
	v_mov_b32_e32 v85, 1.0
	v_mov_b32_e32 v86, 1.0
	v_mov_b32_e32 v87, 1.0
	v_mov_b32_e32 v88, 1.0
	v_mov_b32_e32 v89, 1.0
	v_mov_b32_e32 v90, 1.0
	v_mov_b32_e32 v91, 1.0
	s_and_b64 vcc, exec, s[26:27]
	s_cbranch_vccnz .Lprep_in_nogain
	v_lshl_add_u64 v[80:81], v[48:49], 2, s[56:57]
	global_load_dwordx4 v[84:87], v[80:81], off
	global_load_dwordx4 v[88:91], v[80:81], off offset:16
.Lprep_in_nogain:
	s_waitcnt vmcnt(0)
	v_mul_f32_e32 v24, v24, v84
	v_mul_f32_e32 v52, v52, v85
	v_mul_f32_e32 v53, v53, v86
	v_mul_f32_e32 v54, v54, v87
	v_mul_f32_e32 v55, v55, v88
	v_mul_f32_e32 v62, v62, v89
	v_mul_f32_e32 v63, v63, v90
	v_mul_f32_e32 v64, v64, v91
	s_branch .LBB0_21

; #define SBAR() __builtin_amdgcn_sched_barrier(0)
; template <int DQK, int NQR>
; DEV void qkt(f32x16& p0, f32x16& p1, const char* Ks, const bf16x8* qr, const char* qlds_, int r32, int hi) {
;   constexpr int KROW = ACfg<DQK>::KROW;
;   unsigned qa = (unsigned)(uintptr_t)qlds_; asm volatile("" : "+v"(qa));
;   const __attribute__((address_space(3))) char* qlds = (const __attribute__((address_space(3))) char*)qa;
; #pragma unroll
;   for (int r = 0; r < 16; ++r) { p0[r] = 0.f; p1[r] = 0.f; }
; #pragma unroll
;   for (int d0 = 0; d0 < DQK / 16; ++d0) {
;     const int cb = (d0 * 16 + hi * 8) * 2;
;     bf16x8 b0 = *reinterpret_cast<const bf16x8*>(Ks + r32 * KROW + cb);
;     bf16x8 b1 = *reinterpret_cast<const bf16x8*>(Ks + (32 + r32) * KROW + cb);
;     bf16x8 q;
;     if (d0 < NQR) q = qr[d0 < NQR ? d0 : 0]; else q = *reinterpret_cast<const __attribute__((address_space(3))) bf16x8*>(qlds + (d0 - NQR) * 1024);
;     p0 = __builtin_amdgcn_mfma_f32_32x32x16_bf16(b0, q, p0, 0, 0, 0);
;     p1 = __builtin_amdgcn_mfma_f32_32x32x16_bf16(b1, q, p1, 0, 0, 0);
;     if (NQR < DQK / 16 && (d0 & 3) == 3) SBAR();
;   }
; }
.LBB0_461:
	s_and_b32 s18, s24, 1
	s_mul_i32 s2, s18, 0x6400
	v_add_u32_e32 v202, s2, v186
	ds_read_b128 v[188:191], v202 offset:32768
	ds_read_b128 v[198:201], v202 offset:45568
	ds_read_b128 v[214:217], v202 offset:32800
	ds_read_b128 v[218:221], v202 offset:45600
	ds_read_b128 v[222:225], v202 offset:32832
	ds_read_b128 v[242:245], v202 offset:45632
	global_load_dwordx4 v[144:147], v[246:247], off
	global_load_dwordx4 v[148:151], v[170:171], off
	global_load_dwordx4 v[152:155], v[164:165], off
	global_load_dwordx4 v[156:159], v[166:167], off
	global_load_dwordx4 v[160:163], v[168:169], off
	s_waitcnt lgkmcnt(4)
	v_mfma_f32_32x32x16_bf16 v[80:95], v[188:191], v[140:143], v[226:241]
	v_mfma_f32_32x32x16_bf16 v[64:79], v[198:201], v[140:143], v[226:241]
	ds_read_b128 v[188:191], v202 offset:32864
	ds_read_b128 v[198:201], v202 offset:45664
	s_waitcnt lgkmcnt(4)
	v_mfma_f32_32x32x16_bf16 v[80:95], v[214:217], v[136:139], v[80:95]
	v_mfma_f32_32x32x16_bf16 v[64:79], v[218:221], v[136:139], v[64:79]
	ds_read_b128 v[214:217], v202 offset:32896
	ds_read_b128 v[218:221], v202 offset:45696
	s_waitcnt lgkmcnt(4)
	v_mfma_f32_32x32x16_bf16 v[80:95], v[222:225], v[132:135], v[80:95]
	v_mfma_f32_32x32x16_bf16 v[64:79], v[242:245], v[132:135], v[64:79]
	ds_read_b128 v[222:225], v202 offset:32928
	ds_read_b128 v[242:245], v202 offset:45728
	s_waitcnt lgkmcnt(4)
	v_mfma_f32_32x32x16_bf16 v[80:95], v[188:191], v[128:131], v[80:95]
	v_mfma_f32_32x32x16_bf16 v[64:79], v[198:201], v[128:131], v[64:79]
	ds_read_b128 v[188:191], v202 offset:32960
	ds_read_b128 v[198:201], v202 offset:45760
	s_waitcnt lgkmcnt(4)
	v_mfma_f32_32x32x16_bf16 v[80:95], v[214:217], v[124:127], v[80:95]
	v_mfma_f32_32x32x16_bf16 v[64:79], v[218:221], v[124:127], v[64:79]
	ds_read_b128 v[214:217], v202 offset:32992
	ds_read_b128 v[218:221], v202 offset:45792
	s_waitcnt lgkmcnt(4)
	v_mfma_f32_32x32x16_bf16 v[80:95], v[222:225], v[120:123], v[80:95]
	v_mfma_f32_32x32x16_bf16 v[64:79], v[242:245], v[120:123], v[64:79]
	ds_read_b128 v[222:225], v202 offset:33024
	ds_read_b128 v[242:245], v202 offset:45824
	s_waitcnt lgkmcnt(4)
	v_mfma_f32_32x32x16_bf16 v[80:95], v[188:191], v[116:119], v[80:95]
	v_mfma_f32_32x32x16_bf16 v[64:79], v[198:201], v[116:119], v[64:79]
	ds_read_b128 v[188:191], v202 offset:33056
	ds_read_b128 v[198:201], v202 offset:45856
	s_waitcnt lgkmcnt(4)
	v_mfma_f32_32x32x16_bf16 v[80:95], v[214:217], v[112:115], v[80:95]
	v_mfma_f32_32x32x16_bf16 v[64:79], v[218:221], v[112:115], v[64:79]
	ds_read_b128 v[214:217], v202 offset:33088
	ds_read_b128 v[218:221], v202 offset:45888
	s_waitcnt lgkmcnt(4)
	v_mfma_f32_32x32x16_bf16 v[80:95], v[222:225], v[108:111], v[80:95]
	v_mfma_f32_32x32x16_bf16 v[64:79], v[242:245], v[108:111], v[64:79]
	ds_read_b128 v[222:225], v202 offset:33120
	ds_read_b128 v[242:245], v202 offset:45920
	s_bitcmp0_b32 s100, 0
	s_cbranch_scc1 .Lmla_qk_lead
	s_waitcnt vmcnt(0)
	s_add_i32 s3, s101, 1
	s_cmp_eq_u32 s3, 3
	s_cselect_b32 s3, 0, s3
	s_lshl_b32 s2, s3, 14
	s_cmp_eq_u32 s3, 2
	s_cselect_b32 s3, 0x15000, s2
	s_xor_b32 s2, s18, 1
	s_mul_i32 s2, s2, 0x6400
	v_add_u32_e32 v202, s3, v179
	v_add_u32_e32 v203, s3, v180
	v_add_u32_e32 v213, s2, v182
	ds_write_b128 v202, v[144:147]
	ds_write_b128 v203, v[148:151]
	ds_write_b128 v213, v[152:155] offset:32768
	v_add_u32_e32 v202, s2, v183
	v_add_u32_e32 v203, s2, v184
	ds_write_b128 v202, v[156:159] offset:32768
	ds_write_b128 v203, v[160:163] offset:32768
	s_waitcnt lgkmcnt(9)
	v_mfma_f32_32x32x16_bf16 v[80:95], v[188:191], v[104:107], v[80:95]
	v_mfma_f32_32x32x16_bf16 v[64:79], v[198:201], v[104:107], v[64:79]
	s_waitcnt lgkmcnt(7)
	v_mfma_f32_32x32x16_bf16 v[80:95], v[214:217], v[100:103], v[80:95]
	v_mfma_f32_32x32x16_bf16 v[64:79], v[218:221], v[100:103], v[64:79]
	s_waitcnt lgkmcnt(5)
	v_mfma_f32_32x32x16_bf16 v[80:95], v[222:225], v[96:99], v[80:95]
	v_mfma_f32_32x32x16_bf16 v[64:79], v[242:245], v[96:99], v[64:79]
	s_waitcnt lgkmcnt(0)
	s_barrier
	s_nop 7
	s_nop 0
	s_branch .Lmla_lead_mid
.Lmla_qk_lead:
	s_waitcnt lgkmcnt(4)
	v_mfma_f32_32x32x16_bf16 v[80:95], v[188:191], v[104:107], v[80:95]
	v_mfma_f32_32x32x16_bf16 v[64:79], v[198:201], v[104:107], v[64:79]
	s_waitcnt lgkmcnt(2)
	v_mfma_f32_32x32x16_bf16 v[80:95], v[214:217], v[100:103], v[80:95]
	v_mfma_f32_32x32x16_bf16 v[64:79], v[218:221], v[100:103], v[64:79]
	s_waitcnt lgkmcnt(0)
	v_mfma_f32_32x32x16_bf16 v[80:95], v[222:225], v[96:99], v[80:95]
	v_mfma_f32_32x32x16_bf16 v[64:79], v[242:245], v[96:99], v[64:79]
	s_waitcnt vmcnt(0)
	s_add_i32 s3, s101, 1
	s_cmp_eq_u32 s3, 3
	s_cselect_b32 s3, 0, s3
	s_lshl_b32 s2, s3, 14
	s_cmp_eq_u32 s3, 2
	s_cselect_b32 s3, 0x15000, s2
	s_xor_b32 s2, s18, 1
	s_mul_i32 s2, s2, 0x6400
	v_add_u32_e32 v198, s3, v179
	v_add_u32_e32 v199, s3, v180
	v_add_u32_e32 v200, s2, v182
	v_add_u32_e32 v201, s2, v183
	v_add_u32_e32 v202, s2, v184
	ds_write_b128 v198, v[144:147]
	ds_write_b128 v199, v[148:151]
	ds_write_b128 v200, v[152:155] offset:32768
	ds_write_b128 v201, v[156:159] offset:32768
	ds_write_b128 v202, v[160:163] offset:32768
